# NSA window+selected loops: QK MFMAs of tile i woven into softmax VALU of tile i-1 (spaced, counted lgkmcnt); nt hint on proj GEMM epilogue stores
# speedup vs baseline: 1.4650x; 1.4650x over previous
; #define PG8_STAGE(bufoff, gbase, voff) do { _Pragma("unroll") for (int _i = 0; _i < 2; ++_i) \
;         __builtin_amdgcn_global_load_lds((const unsigned*)((const char*)(gbase) + (voff)[_i]), (LAS unsigned*)(lds + (bufoff) + ldsw + _i * 8192), 16, 0, 0); } while (0)
; #define PG8_LDA(dst, b, h) do { _Pragma("unroll") for (int m = 0; m < 4; ++m) _Pragma("unroll") for (int k = 0; k < 2; ++k) dst[m][k] = *(const LAS bf16x8*)(lds + PG8_SA(b, h) + aoff + m * 2048 + k * 1024); } while (0)
; #define PG8_LDB(dst, b, h) do { _Pragma("unroll") for (int n = 0; n < 2; ++n) _Pragma("unroll") for (int k = 0; k < 2; ++k) dst[n][k] = *(const LAS bf16x8*)(lds + PG8_SB(b, h) + boff + n * 2048 + k * 1024); } while (0)
; #define PG8_MMA(ai, bj, At, Bt) do { __builtin_amdgcn_s_setprio(1); _Pragma("unroll") for (int m = 0; m < 4; ++m) _Pragma("unroll") for (int n = 0; n < 2; ++n) _Pragma("unroll") for (int k = 0; k < 2; ++k) \
;         acc[ai][bj][m][n] = __builtin_amdgcn_mfma_f32_16x16x32_bf16(Bt[n][k], At[m][k], acc[ai][bj][m][n], 0, 0, 0); __builtin_amdgcn_s_setprio(0); } while (0)
; #define PG8_WAIT_V(n) asm volatile("s_waitcnt vmcnt(" #n ")" ::: "memory")
; template <class Epi>
; DI void gemm_phase(LAS unsigned char* lds, const Gemm g, const StaticOrder& S, const Epi& E) {
;     ...
;         for (int t = 0; t < nt; t += 2) {
;             const bool last = (t == nt - 2);
;             const char* a1 = cA + (size_t)(t + 1) * kstep;
;             const char* a2 = last ? nA : cA + (size_t)(t + 2) * kstep; const char* b2 = last ? nB : cB + (size_t)(t + 2) * kstep;
;             const char* a3 = a2 + kstep; const char* b3 = b2 + kstep;
;             if constexpr (Epi::HAS_MID) { if (t == Epi::MID_T) E.mid(acc, cur, wr, wc, fr, fq); }
;             PG8_LDB(B0, 0, 0); PG8_SCHED; PG8_LDA(At, 0, 0); PG8_STAGE(PG8_SA(1, 1), a1 + hstepA, voffA);
;             PG8_WAIT_L(8); PG8_BAR; PG8_WAIT_L(0); PG8_MMA(0, 0, At, B0); PG8_BAR; PG8_SCHED;
;             PG8_LDB(B1, 0, 1); PG8_STAGE(PG8_SB(0, 0), b2, voffB);
;             PG8_BAR; PG8_WAIT_L(0); PG8_MMA(0, 1, At, B1); PG8_BAR;
;             PG8_LDA(At, 0, 1); PG8_STAGE(PG8_SA(0, 0), a2, voffA);
;             PG8_BAR; PG8_WAIT_L(0); PG8_MMA(1, 0, At, B0); PG8_BAR; PG8_SCHED;
;             PG8_STAGE(PG8_SB(0, 1), b2 + hstepB, voffB);
;             PG8_WAIT_V(6); PG8_BAR; PG8_MMA(1, 1, At, B1); PG8_BAR;
.LBB0_113:
	ds_read_b128 v[150:153], v147
	ds_read_b128 v[154:157], v147 offset:1024
	ds_read_b128 v[158:161], v147 offset:2048
	ds_read_b128 v[162:165], v147 offset:3072
	s_add_u32 s0, s52, 0xfff80080
	s_addc_u32 s1, s53, -1
	s_cmp_eq_u32 s83, 28
	s_cselect_b32 s57, s47, s1
	s_cselect_b32 s56, s79, s0
	s_cselect_b32 s55, s17, s82
	s_cselect_b32 s54, s80, s81
	v_lshl_add_u64 v[170:171], s[52:53], 0, v[136:137]
	s_add_i32 m0, s9, 0xc000
	ds_read_b128 v[166:169], v148
	ds_read_b128 v[174:177], v148 offset:1024
	ds_read_b128 v[178:181], v148 offset:2048
	ds_read_b128 v[182:185], v148 offset:3072
	ds_read_b128 v[186:189], v148 offset:4096
	ds_read_b128 v[190:193], v148 offset:5120
	ds_read_b128 v[194:197], v148 offset:6144
	ds_read_b128 v[198:201], v148 offset:7168
	global_load_lds_dwordx4 v[170:171], off
	v_lshl_add_u64 v[170:171], s[52:53], 0, v[138:139]
	s_add_i32 m0, s9, 0xe000
	s_nop 0
	global_load_lds_dwordx4 v[170:171], off
	s_waitcnt lgkmcnt(8)
	s_barrier
	s_waitcnt lgkmcnt(0)
	s_setprio 1
	s_waitcnt lgkmcnt(0)
	v_mfma_f32_16x16x32_bf16 v[124:127], v[150:153], v[166:169], v[124:127]
	v_mfma_f32_16x16x32_bf16 v[120:123], v[158:161], v[166:169], v[120:123]
	v_mfma_f32_16x16x32_bf16 v[116:119], v[150:153], v[178:181], v[116:119]
	v_mfma_f32_16x16x32_bf16 v[112:115], v[158:161], v[178:181], v[112:115]
	v_mfma_f32_16x16x32_bf16 v[100:103], v[150:153], v[186:189], v[100:103]
	v_mfma_f32_16x16x32_bf16 v[96:99], v[158:161], v[186:189], v[96:99]
	v_mfma_f32_16x16x32_bf16 v[84:87], v[150:153], v[194:197], v[84:87]
	v_mfma_f32_16x16x32_bf16 v[80:83], v[158:161], v[194:197], v[80:83]
	v_mfma_f32_16x16x32_bf16 v[124:127], v[154:157], v[174:177], v[124:127]
	v_mfma_f32_16x16x32_bf16 v[120:123], v[162:165], v[174:177], v[120:123]
	v_mfma_f32_16x16x32_bf16 v[116:119], v[154:157], v[182:185], v[116:119]
	v_mfma_f32_16x16x32_bf16 v[112:115], v[162:165], v[182:185], v[112:115]
	v_mfma_f32_16x16x32_bf16 v[100:103], v[154:157], v[190:193], v[100:103]
	v_mfma_f32_16x16x32_bf16 v[96:99], v[162:165], v[190:193], v[96:99]
	v_mfma_f32_16x16x32_bf16 v[84:87], v[154:157], v[198:201], v[84:87]
	v_mfma_f32_16x16x32_bf16 v[80:83], v[162:165], v[198:201], v[80:83]
	s_setprio 0
	s_barrier
	s_add_i32 s0, s75, s58
	v_lshl_add_u64 v[170:171], s[54:55], 0, v[132:133]
	s_mov_b32 m0, s0
	ds_read_b128 v[202:205], v149
	ds_read_b128 v[206:209], v149 offset:1024
	ds_read_b128 v[210:213], v149 offset:2048
	ds_read_b128 v[216:219], v149 offset:3072
	global_load_lds_dwordx4 v[170:171], off
	v_lshl_add_u64 v[220:221], s[54:55], 0, v[128:129]
	s_add_i32 m0, s0, 0x2000
	s_nop 0
	global_load_lds_dwordx4 v[220:221], off
	s_barrier
	s_waitcnt lgkmcnt(0)
	s_setprio 1
	s_waitcnt lgkmcnt(0)
	v_mfma_f32_16x16x32_bf16 v[108:111], v[202:205], v[166:169], v[108:111]
	v_mfma_f32_16x16x32_bf16 v[104:107], v[210:213], v[166:169], v[104:107]
	v_mfma_f32_16x16x32_bf16 v[92:95], v[202:205], v[178:181], v[92:95]
	v_mfma_f32_16x16x32_bf16 v[88:91], v[210:213], v[178:181], v[88:91]
	v_mfma_f32_16x16x32_bf16 v[76:79], v[202:205], v[186:189], v[76:79]
	v_mfma_f32_16x16x32_bf16 v[72:75], v[210:213], v[186:189], v[72:75]
	v_mfma_f32_16x16x32_bf16 v[68:71], v[202:205], v[194:197], v[68:71]
	v_mfma_f32_16x16x32_bf16 v[64:67], v[210:213], v[194:197], v[64:67]
	v_mfma_f32_16x16x32_bf16 v[108:111], v[206:209], v[174:177], v[108:111]
	v_mfma_f32_16x16x32_bf16 v[104:107], v[216:219], v[174:177], v[104:107]
	v_mfma_f32_16x16x32_bf16 v[92:95], v[206:209], v[182:185], v[92:95]
	v_mfma_f32_16x16x32_bf16 v[88:91], v[216:219], v[182:185], v[88:91]
	v_mfma_f32_16x16x32_bf16 v[76:79], v[206:209], v[190:193], v[76:79]
	v_mfma_f32_16x16x32_bf16 v[72:75], v[216:219], v[190:193], v[72:75]
	v_mfma_f32_16x16x32_bf16 v[68:71], v[206:209], v[198:201], v[68:71]
	v_mfma_f32_16x16x32_bf16 v[64:67], v[216:219], v[198:201], v[64:67]
	s_setprio 0
	s_mov_b32 m0, s9
	v_lshl_add_u64 v[222:223], s[56:57], 0, v[134:135]
	s_barrier
	ds_read_b128 v[166:169], v148 offset:16384
	ds_read_b128 v[174:177], v148 offset:17408
	ds_read_b128 v[178:181], v148 offset:18432
	ds_read_b128 v[182:185], v148 offset:19456
	ds_read_b128 v[186:189], v148 offset:20480
	ds_read_b128 v[190:193], v148 offset:21504
	ds_read_b128 v[194:197], v148 offset:22528
	ds_read_b128 v[198:201], v148 offset:23552
	global_load_lds_dwordx4 v[222:223], off
	v_lshl_add_u64 v[224:225], s[56:57], 0, v[130:131]
	s_mov_b32 m0, s61
	s_nop 0
	global_load_lds_dwordx4 v[224:225], off
	s_barrier
	s_waitcnt lgkmcnt(0)
	s_setprio 1
	s_waitcnt lgkmcnt(0)
	v_mfma_f32_16x16x32_bf16 v[60:63], v[150:153], v[166:169], v[60:63]
	v_mfma_f32_16x16x32_bf16 v[56:59], v[158:161], v[166:169], v[56:59]
	v_mfma_f32_16x16x32_bf16 v[52:55], v[150:153], v[178:181], v[52:55]
	v_mfma_f32_16x16x32_bf16 v[48:51], v[158:161], v[178:181], v[48:51]
	v_mfma_f32_16x16x32_bf16 v[36:39], v[150:153], v[186:189], v[36:39]
	v_mfma_f32_16x16x32_bf16 v[32:35], v[158:161], v[186:189], v[32:35]
	v_mfma_f32_16x16x32_bf16 v[20:23], v[150:153], v[194:197], v[20:23]
	v_mfma_f32_16x16x32_bf16 v[16:19], v[158:161], v[194:197], v[16:19]
	v_mfma_f32_16x16x32_bf16 v[60:63], v[154:157], v[174:177], v[60:63]
	v_mfma_f32_16x16x32_bf16 v[56:59], v[162:165], v[174:177], v[56:59]
	v_mfma_f32_16x16x32_bf16 v[52:55], v[154:157], v[182:185], v[52:55]
	v_mfma_f32_16x16x32_bf16 v[48:51], v[162:165], v[182:185], v[48:51]
	v_mfma_f32_16x16x32_bf16 v[36:39], v[154:157], v[190:193], v[36:39]
	v_mfma_f32_16x16x32_bf16 v[32:35], v[162:165], v[190:193], v[32:35]
	v_mfma_f32_16x16x32_bf16 v[20:23], v[154:157], v[198:201], v[20:23]
	v_mfma_f32_16x16x32_bf16 v[16:19], v[162:165], v[198:201], v[16:19]
	s_setprio 0
	s_barrier
; #define PG8_STAGE(bufoff, gbase, voff) do { _Pragma("unroll") for (int _i = 0; _i < 2; ++_i) \
;         __builtin_amdgcn_global_load_lds((const unsigned*)((const char*)(gbase) + (voff)[_i]), (LAS unsigned*)(lds + (bufoff) + ldsw + _i * 8192), 16, 0, 0); } while (0)
; #define PG8_LDA(dst, b, h) do { _Pragma("unroll") for (int m = 0; m < 4; ++m) _Pragma("unroll") for (int k = 0; k < 2; ++k) dst[m][k] = *(const LAS bf16x8*)(lds + PG8_SA(b, h) + aoff + m * 2048 + k * 1024); } while (0)
; #define PG8_LDB(dst, b, h) do { _Pragma("unroll") for (int n = 0; n < 2; ++n) _Pragma("unroll") for (int k = 0; k < 2; ++k) dst[n][k] = *(const LAS bf16x8*)(lds + PG8_SB(b, h) + boff + n * 2048 + k * 1024); } while (0)
; #define PG8_MMA(ai, bj, At, Bt) do { __builtin_amdgcn_s_setprio(1); _Pragma("unroll") for (int m = 0; m < 4; ++m) _Pragma("unroll") for (int n = 0; n < 2; ++n) _Pragma("unroll") for (int k = 0; k < 2; ++k) \
;         acc[ai][bj][m][n] = __builtin_amdgcn_mfma_f32_16x16x32_bf16(Bt[n][k], At[m][k], acc[ai][bj][m][n], 0, 0, 0); __builtin_amdgcn_s_setprio(0); } while (0)
; #define PG8_WAIT_V(n) asm volatile("s_waitcnt vmcnt(" #n ")" ::: "memory")
; #define PG8_WAIT_L(n) asm volatile("s_waitcnt lgkmcnt(" #n ")" ::: "memory")
; #define PG8_BAR __builtin_amdgcn_s_barrier()
; #define PG8_SCHED __builtin_amdgcn_sched_barrier(0)
; template <class Epi>
; DI void gemm_phase(LAS unsigned char* lds, const Gemm g, const StaticOrder& S, const Epi& E) {
;     ...
;             PG8_LDA(At, 0, 1); PG8_STAGE(PG8_SA(0, 0), a2, voffA);
;             PG8_BAR; PG8_WAIT_L(0); PG8_MMA(1, 0, At, B0); PG8_BAR; PG8_SCHED;
;             PG8_STAGE(PG8_SB(0, 1), b2 + hstepB, voffB);
;             PG8_WAIT_V(6); PG8_BAR; PG8_MMA(1, 1, At, B1); PG8_BAR;
;             PG8_LDB(B0, 1, 0); PG8_SCHED; PG8_LDA(At, 1, 0); PG8_STAGE(PG8_SA(0, 1), a2 + hstepA, voffA);
;             PG8_WAIT_L(8); PG8_BAR; PG8_WAIT_L(0); PG8_MMA(0, 0, At, B0); PG8_BAR; PG8_SCHED;
;             PG8_LDB(B1, 1, 1); PG8_STAGE(PG8_SB(1, 0), b3, voffB);
;             PG8_BAR; PG8_WAIT_L(0); PG8_MMA(0, 1, At, B1); PG8_BAR;
;             PG8_LDA(At, 1, 1); PG8_STAGE(PG8_SA(1, 0), a3, voffA);
;             PG8_BAR; PG8_WAIT_L(0); PG8_MMA(1, 0, At, B0); PG8_BAR; PG8_SCHED;
	s_add_u32 s0, s54, 0x80000
	s_addc_u32 s1, s55, 0
	s_add_i32 s84, s76, s58
	v_lshl_add_u64 v[150:151], s[0:1], 0, v[132:133]
	s_mov_b32 m0, s84
	s_nop 0
	global_load_lds_dwordx4 v[150:151], off
	v_lshl_add_u64 v[150:151], s[0:1], 0, v[128:129]
	s_add_i32 m0, s84, 0x2000
	s_nop 0
	global_load_lds_dwordx4 v[150:151], off
	s_waitcnt vmcnt(6)
	s_barrier
	s_setprio 1
	v_mfma_f32_16x16x32_bf16 v[44:47], v[202:205], v[166:169], v[44:47]
	v_mfma_f32_16x16x32_bf16 v[40:43], v[210:213], v[166:169], v[40:43]
	v_mfma_f32_16x16x32_bf16 v[28:31], v[202:205], v[178:181], v[28:31]
	v_mfma_f32_16x16x32_bf16 v[24:27], v[210:213], v[178:181], v[24:27]
	v_mfma_f32_16x16x32_bf16 v[12:15], v[202:205], v[186:189], v[12:15]
	v_mfma_f32_16x16x32_bf16 v[8:11], v[210:213], v[186:189], v[8:11]
	v_mfma_f32_16x16x32_bf16 v[4:7], v[202:205], v[194:197], v[4:7]
	v_mfma_f32_16x16x32_bf16 v[0:3], v[210:213], v[194:197], v[0:3]
	v_mfma_f32_16x16x32_bf16 v[44:47], v[206:209], v[174:177], v[44:47]
	v_mfma_f32_16x16x32_bf16 v[40:43], v[216:219], v[174:177], v[40:43]
	v_mfma_f32_16x16x32_bf16 v[28:31], v[206:209], v[182:185], v[28:31]
	v_mfma_f32_16x16x32_bf16 v[24:27], v[216:219], v[182:185], v[24:27]
	v_mfma_f32_16x16x32_bf16 v[12:15], v[206:209], v[190:193], v[12:15]
	v_mfma_f32_16x16x32_bf16 v[8:11], v[216:219], v[190:193], v[8:11]
	v_mfma_f32_16x16x32_bf16 v[4:7], v[206:209], v[198:201], v[4:7]
	v_mfma_f32_16x16x32_bf16 v[0:3], v[216:219], v[198:201], v[0:3]
	s_setprio 0
	s_add_i32 s84, 0, 0x18000
	v_add_u32_e32 v162, s84, v145
	s_barrier
	ds_read_b128 v[150:153], v162
	ds_read_b128 v[154:157], v162 offset:1024
	ds_read_b128 v[158:161], v162 offset:2048
	ds_read_b128 v[162:165], v162 offset:3072
	s_add_u32 s0, s56, 0x80000
	s_addc_u32 s1, s57, 0
	s_mov_b32 m0, s68
	v_lshl_add_u64 v[202:203], s[0:1], 0, v[134:135]
	ds_read_b128 v[166:169], v148 offset:32768
	ds_read_b128 v[174:177], v148 offset:33792
	ds_read_b128 v[178:181], v148 offset:34816
	ds_read_b128 v[182:185], v148 offset:35840
	ds_read_b128 v[186:189], v148 offset:36864
	ds_read_b128 v[190:193], v148 offset:37888
	ds_read_b128 v[194:197], v148 offset:38912
	ds_read_b128 v[198:201], v148 offset:39936
	global_load_lds_dwordx4 v[202:203], off
	v_lshl_add_u64 v[202:203], s[0:1], 0, v[130:131]
	s_mov_b32 m0, s69
	s_nop 0
	global_load_lds_dwordx4 v[202:203], off
	s_waitcnt lgkmcnt(8)
	s_barrier
	s_waitcnt lgkmcnt(0)
	s_setprio 1
	s_waitcnt lgkmcnt(0)
	v_mfma_f32_16x16x32_bf16 v[124:127], v[150:153], v[166:169], v[124:127]
	v_mfma_f32_16x16x32_bf16 v[120:123], v[158:161], v[166:169], v[120:123]
	v_mfma_f32_16x16x32_bf16 v[116:119], v[150:153], v[178:181], v[116:119]
	v_mfma_f32_16x16x32_bf16 v[112:115], v[158:161], v[178:181], v[112:115]
	v_mfma_f32_16x16x32_bf16 v[100:103], v[150:153], v[186:189], v[100:103]
	v_mfma_f32_16x16x32_bf16 v[96:99], v[158:161], v[186:189], v[96:99]
	v_mfma_f32_16x16x32_bf16 v[84:87], v[150:153], v[194:197], v[84:87]
	v_mfma_f32_16x16x32_bf16 v[80:83], v[158:161], v[194:197], v[80:83]
	v_mfma_f32_16x16x32_bf16 v[124:127], v[154:157], v[174:177], v[124:127]
	v_mfma_f32_16x16x32_bf16 v[120:123], v[162:165], v[174:177], v[120:123]
	v_mfma_f32_16x16x32_bf16 v[116:119], v[154:157], v[182:185], v[116:119]
	v_mfma_f32_16x16x32_bf16 v[112:115], v[162:165], v[182:185], v[112:115]
	v_mfma_f32_16x16x32_bf16 v[100:103], v[154:157], v[190:193], v[100:103]
	v_mfma_f32_16x16x32_bf16 v[96:99], v[162:165], v[190:193], v[96:99]
	v_mfma_f32_16x16x32_bf16 v[84:87], v[154:157], v[198:201], v[84:87]
	v_mfma_f32_16x16x32_bf16 v[80:83], v[162:165], v[198:201], v[80:83]
	s_setprio 0
	s_barrier
	s_add_i32 s56, 0, 0x1c000
	s_add_i32 s0, s84, s58
	v_add_u32_e32 v172, s56, v145
	v_lshl_add_u64 v[170:171], v[170:171], 0, s[4:5]
	s_mov_b32 m0, s0
	ds_read_b128 v[202:205], v172
	ds_read_b128 v[206:209], v172 offset:1024
	ds_read_b128 v[210:213], v172 offset:2048
	ds_read_b128 v[216:219], v172 offset:3072
	global_load_lds_dwordx4 v[170:171], off
	v_lshl_add_u64 v[170:171], v[220:221], 0, s[4:5]
	s_add_i32 m0, s0, 0x2000
	s_nop 0
	global_load_lds_dwordx4 v[170:171], off
	s_barrier
	s_waitcnt lgkmcnt(0)
	s_setprio 1
	s_waitcnt lgkmcnt(0)
	v_mfma_f32_16x16x32_bf16 v[108:111], v[202:205], v[166:169], v[108:111]
	v_mfma_f32_16x16x32_bf16 v[104:107], v[210:213], v[166:169], v[104:107]
	v_mfma_f32_16x16x32_bf16 v[92:95], v[202:205], v[178:181], v[92:95]
	v_mfma_f32_16x16x32_bf16 v[88:91], v[210:213], v[178:181], v[88:91]
	v_mfma_f32_16x16x32_bf16 v[76:79], v[202:205], v[186:189], v[76:79]
	v_mfma_f32_16x16x32_bf16 v[72:75], v[210:213], v[186:189], v[72:75]
	v_mfma_f32_16x16x32_bf16 v[68:71], v[202:205], v[194:197], v[68:71]
	v_mfma_f32_16x16x32_bf16 v[64:67], v[210:213], v[194:197], v[64:67]
	v_mfma_f32_16x16x32_bf16 v[108:111], v[206:209], v[174:177], v[108:111]
	v_mfma_f32_16x16x32_bf16 v[104:107], v[216:219], v[174:177], v[104:107]
	v_mfma_f32_16x16x32_bf16 v[92:95], v[206:209], v[182:185], v[92:95]
	v_mfma_f32_16x16x32_bf16 v[88:91], v[216:219], v[182:185], v[88:91]
	v_mfma_f32_16x16x32_bf16 v[76:79], v[206:209], v[190:193], v[76:79]
	v_mfma_f32_16x16x32_bf16 v[72:75], v[216:219], v[190:193], v[72:75]
	v_mfma_f32_16x16x32_bf16 v[68:71], v[206:209], v[198:201], v[68:71]
	v_mfma_f32_16x16x32_bf16 v[64:67], v[216:219], v[198:201], v[64:67]
	s_setprio 0
	s_mov_b32 m0, s71
	v_lshl_add_u64 v[170:171], v[222:223], 0, s[4:5]
	s_barrier
	ds_read_b128 v[166:169], v148 offset:49152
	ds_read_b128 v[174:177], v148 offset:50176
	ds_read_b128 v[178:181], v148 offset:51200
	ds_read_b128 v[182:185], v148 offset:52224
	ds_read_b128 v[186:189], v148 offset:53248
	ds_read_b128 v[190:193], v148 offset:54272
	ds_read_b128 v[194:197], v148 offset:55296
	ds_read_b128 v[198:201], v148 offset:56320
	global_load_lds_dwordx4 v[170:171], off
	v_lshl_add_u64 v[170:171], v[224:225], 0, s[4:5]
	s_mov_b32 m0, s72
	s_nop 0
	global_load_lds_dwordx4 v[170:171], off
	s_barrier
; #define PG8_STAGE(bufoff, gbase, voff) do { _Pragma("unroll") for (int _i = 0; _i < 2; ++_i) \
;         __builtin_amdgcn_global_load_lds((const unsigned*)((const char*)(gbase) + (voff)[_i]), (LAS unsigned*)(lds + (bufoff) + ldsw + _i * 8192), 16, 0, 0); } while (0)
; #define PG8_LDA(dst, b, h) do { _Pragma("unroll") for (int m = 0; m < 4; ++m) _Pragma("unroll") for (int k = 0; k < 2; ++k) dst[m][k] = *(const LAS bf16x8*)(lds + PG8_SA(b, h) + aoff + m * 2048 + k * 1024); } while (0)
; #define PG8_MMA(ai, bj, At, Bt) do { __builtin_amdgcn_s_setprio(1); _Pragma("unroll") for (int m = 0; m < 4; ++m) _Pragma("unroll") for (int n = 0; n < 2; ++n) _Pragma("unroll") for (int k = 0; k < 2; ++k) \
;         acc[ai][bj][m][n] = __builtin_amdgcn_mfma_f32_16x16x32_bf16(Bt[n][k], At[m][k], acc[ai][bj][m][n], 0, 0, 0); __builtin_amdgcn_s_setprio(0); } while (0)
; #define PG8_WAIT_V(n) asm volatile("s_waitcnt vmcnt(" #n ")" ::: "memory")
; #define PG8_WAIT_L(n) asm volatile("s_waitcnt lgkmcnt(" #n ")" ::: "memory")
; #define PG8_BAR __builtin_amdgcn_s_barrier()
; #define PG8_SCHED __builtin_amdgcn_sched_barrier(0)
; template <class Epi>
; DI void gemm_phase(LAS unsigned char* lds, const Gemm g, const StaticOrder& S, const Epi& E) {
;     ...
;             PG8_BAR; PG8_WAIT_L(0); PG8_MMA(0, 1, At, B1); PG8_BAR;
;             PG8_LDA(At, 1, 1); PG8_STAGE(PG8_SA(1, 0), a3, voffA);
;             PG8_BAR; PG8_WAIT_L(0); PG8_MMA(1, 0, At, B0); PG8_BAR; PG8_SCHED;
;             PG8_STAGE(PG8_SB(1, 1), b3 + hstepB, voffB);
;             PG8_WAIT_V(6); PG8_BAR; PG8_MMA(1, 1, At, B1); PG8_BAR;
;         }
	s_waitcnt lgkmcnt(0)
	s_setprio 1
	s_waitcnt lgkmcnt(0)
	v_mfma_f32_16x16x32_bf16 v[60:63], v[150:153], v[166:169], v[60:63]
	v_mfma_f32_16x16x32_bf16 v[56:59], v[158:161], v[166:169], v[56:59]
	v_mfma_f32_16x16x32_bf16 v[52:55], v[150:153], v[178:181], v[52:55]
	v_mfma_f32_16x16x32_bf16 v[48:51], v[158:161], v[178:181], v[48:51]
	v_mfma_f32_16x16x32_bf16 v[36:39], v[150:153], v[186:189], v[36:39]
	v_mfma_f32_16x16x32_bf16 v[32:35], v[158:161], v[186:189], v[32:35]
	v_mfma_f32_16x16x32_bf16 v[20:23], v[150:153], v[194:197], v[20:23]
	v_mfma_f32_16x16x32_bf16 v[16:19], v[158:161], v[194:197], v[16:19]
	v_mfma_f32_16x16x32_bf16 v[60:63], v[154:157], v[174:177], v[60:63]
	v_mfma_f32_16x16x32_bf16 v[56:59], v[162:165], v[174:177], v[56:59]
	v_mfma_f32_16x16x32_bf16 v[52:55], v[154:157], v[182:185], v[52:55]
	v_mfma_f32_16x16x32_bf16 v[48:51], v[162:165], v[182:185], v[48:51]
	v_mfma_f32_16x16x32_bf16 v[36:39], v[154:157], v[190:193], v[36:39]
	v_mfma_f32_16x16x32_bf16 v[32:35], v[162:165], v[190:193], v[32:35]
	v_mfma_f32_16x16x32_bf16 v[20:23], v[154:157], v[198:201], v[20:23]
	v_mfma_f32_16x16x32_bf16 v[16:19], v[162:165], v[198:201], v[16:19]
	s_setprio 0
	s_barrier
	s_add_u32 s0, s54, 0x80080
	s_addc_u32 s1, s55, 0
	s_add_i32 s54, s56, s58
	v_lshl_add_u64 v[150:151], s[0:1], 0, v[132:133]
	s_mov_b32 m0, s54
	s_nop 0
	global_load_lds_dwordx4 v[150:151], off
	v_lshl_add_u64 v[150:151], s[0:1], 0, v[128:129]
	s_add_i32 m0, s54, 0x2000
	s_nop 0
	global_load_lds_dwordx4 v[150:151], off
	s_waitcnt vmcnt(6)
	s_barrier
	s_setprio 1
	v_mfma_f32_16x16x32_bf16 v[44:47], v[202:205], v[166:169], v[44:47]
	v_mfma_f32_16x16x32_bf16 v[40:43], v[210:213], v[166:169], v[40:43]
	v_mfma_f32_16x16x32_bf16 v[28:31], v[202:205], v[178:181], v[28:31]
	v_mfma_f32_16x16x32_bf16 v[24:27], v[210:213], v[178:181], v[24:27]
	v_mfma_f32_16x16x32_bf16 v[12:15], v[202:205], v[186:189], v[12:15]
	v_mfma_f32_16x16x32_bf16 v[8:11], v[210:213], v[186:189], v[8:11]
	v_mfma_f32_16x16x32_bf16 v[4:7], v[202:205], v[194:197], v[4:7]
	v_mfma_f32_16x16x32_bf16 v[0:3], v[210:213], v[194:197], v[0:3]
	v_mfma_f32_16x16x32_bf16 v[44:47], v[206:209], v[174:177], v[44:47]
	v_mfma_f32_16x16x32_bf16 v[40:43], v[216:219], v[174:177], v[40:43]
	v_mfma_f32_16x16x32_bf16 v[28:31], v[206:209], v[182:185], v[28:31]
	v_mfma_f32_16x16x32_bf16 v[24:27], v[216:219], v[182:185], v[24:27]
	v_mfma_f32_16x16x32_bf16 v[12:15], v[206:209], v[190:193], v[12:15]
	v_mfma_f32_16x16x32_bf16 v[8:11], v[216:219], v[190:193], v[8:11]
	v_mfma_f32_16x16x32_bf16 v[4:7], v[206:209], v[198:201], v[4:7]
	v_mfma_f32_16x16x32_bf16 v[0:3], v[216:219], v[198:201], v[0:3]
	s_setprio 0
	s_add_i32 s83, s83, 2
	s_add_u32 s52, s52, 0x100
	s_addc_u32 s53, s53, 0
	s_add_u32 s81, s81, 0x100
	s_addc_u32 s82, s82, 0
	s_cmp_gt_u32 s83, 29
	s_barrier
	s_cbranch_scc0 .LBB0_113
; DI unsigned pk2(float lo, float hi) { f32x2 v = {lo, hi}; bf16x2_t b = __builtin_convertvector(v, bf16x2_t); return __builtin_bit_cast(unsigned, b); }
;     DI void operator()(const f32x4 (&acc)[2][2][4][2], const Unit& u, int wr, int wc, int fr, int fq) const {
;         const int row0 = u.pm * BM + wr * 64 + fr, col0 = u.pn * BM + wc * 32 + 8 * fq;
; #pragma unroll
;         for (int ai = 0; ai < 2; ++ai)
; #pragma unroll
;             for (int m = 0; m < 4; ++m) { bf16_t* rowp = O + (size_t)(row0 + ai * HALF + m * 16) * ldc + col0;
; #pragma unroll
;                 for (int bj = 0; bj < 2; ++bj) { const f32x4 v0 = acc[ai][bj][m][0], v1 = acc[ai][bj][m][1];
;                     u32x4 w; w.x = pk2(v0[0], v0[1]); w.y = pk2(v0[2], v0[3]); w.z = pk2(v1[0], v1[1]); w.w = pk2(v1[2], v1[3]);
;                     *(u32x4*)(rowp + bj * HALF) = w; } }
;     }
	v_lshl_add_u32 v156, s8, 8, v144
	v_lshl_or_b32 v150, s78, 8, v146
	v_ashrrev_i32_e32 v151, 31, v150
	v_mov_b64_e32 v[152:153], s[30:31]
	v_cvt_pk_bf16_f32 v68, v68, v69
	v_cvt_pk_bf16_f32 v69, v70, v71
	v_cvt_pk_bf16_f32 v70, v64, v65
	v_add_u32_e32 v64, 0x80, v156
	v_mad_i64_i32 v[154:155], s[0:1], v156, s77, v[152:153]
	v_lshlrev_b64 v[150:151], 1, v[150:151]
	v_cvt_pk_bf16_f32 v108, v108, v109
	v_cvt_pk_bf16_f32 v109, v110, v111
	v_cvt_pk_bf16_f32 v110, v104, v105
	v_or_b32_e32 v104, 16, v156
	v_mad_i64_i32 v[64:65], s[0:1], v64, s77, v[152:153]
	v_cvt_pk_bf16_f32 v44, v44, v45
	v_cvt_pk_bf16_f32 v45, v46, v47
	v_cvt_pk_bf16_f32 v46, v40, v41
	v_add_u32_e32 v40, 0x90, v156
	v_lshl_add_u64 v[154:155], v[154:155], 0, v[150:151]
	v_cvt_pk_bf16_f32 v111, v106, v107
	v_mad_i64_i32 v[104:105], s[0:1], v104, s77, v[152:153]
	v_cvt_pk_bf16_f32 v92, v92, v93
	v_cvt_pk_bf16_f32 v93, v94, v95
	v_cvt_pk_bf16_f32 v94, v88, v89
	v_or_b32_e32 v88, 32, v156
	v_lshl_add_u64 v[64:65], v[64:65], 0, v[150:151]
	v_cvt_pk_bf16_f32 v47, v42, v43
	v_mad_i64_i32 v[40:41], s[0:1], v40, s77, v[152:153]
	v_cvt_pk_bf16_f32 v28, v28, v29
	v_cvt_pk_bf16_f32 v29, v30, v31
	v_cvt_pk_bf16_f32 v30, v24, v25
	v_add_u32_e32 v24, 0xa0, v156
	global_store_dwordx4 v[154:155], v[108:111], off offset:256 nt
	v_cvt_pk_bf16_f32 v95, v90, v91
	v_mad_i64_i32 v[88:89], s[0:1], v88, s77, v[152:153]
	v_lshl_add_u64 v[108:109], v[104:105], 0, v[150:151]
	v_cvt_pk_bf16_f32 v76, v76, v77
	v_cvt_pk_bf16_f32 v77, v78, v79
	v_cvt_pk_bf16_f32 v78, v72, v73
	v_or_b32_e32 v72, 48, v156
	global_store_dwordx4 v[64:65], v[44:47], off offset:256 nt
	v_cvt_pk_bf16_f32 v31, v26, v27
	v_mad_i64_i32 v[24:25], s[0:1], v24, s77, v[152:153]
	v_lshl_add_u64 v[44:45], v[40:41], 0, v[150:151]
	v_cvt_pk_bf16_f32 v12, v12, v13
	v_cvt_pk_bf16_f32 v13, v14, v15
	v_cvt_pk_bf16_f32 v14, v8, v9
	v_add_u32_e32 v8, 0xb0, v156
	global_store_dwordx4 v[108:109], v[92:95], off offset:256 nt
	v_cvt_pk_bf16_f32 v79, v74, v75
	v_mad_i64_i32 v[72:73], s[0:1], v72, s77, v[152:153]
	v_lshl_add_u64 v[92:93], v[88:89], 0, v[150:151]
	global_store_dwordx4 v[44:45], v[28:31], off offset:256 nt
	v_cvt_pk_bf16_f32 v15, v10, v11
	v_mad_i64_i32 v[8:9], s[0:1], v8, s77, v[152:153]
	v_lshl_add_u64 v[28:29], v[24:25], 0, v[150:151]
	v_cvt_pk_bf16_f32 v124, v124, v125
	v_cvt_pk_bf16_f32 v125, v126, v127
	v_cvt_pk_bf16_f32 v126, v120, v121
	v_cvt_pk_bf16_f32 v127, v122, v123
	v_cvt_pk_bf16_f32 v104, v116, v117
	v_cvt_pk_bf16_f32 v105, v118, v119
	v_cvt_pk_bf16_f32 v106, v112, v113
	v_cvt_pk_bf16_f32 v107, v114, v115
	v_cvt_pk_bf16_f32 v88, v100, v101
	v_cvt_pk_bf16_f32 v89, v102, v103
	v_cvt_pk_bf16_f32 v90, v96, v97
	v_cvt_pk_bf16_f32 v91, v98, v99
	global_store_dwordx4 v[92:93], v[76:79], off offset:256 nt
	v_cvt_pk_bf16_f32 v74, v80, v81
	v_cvt_pk_bf16_f32 v75, v82, v83
	v_lshl_add_u64 v[76:77], v[72:73], 0, v[150:151]
	v_cvt_pk_bf16_f32 v72, v84, v85
	v_cvt_pk_bf16_f32 v73, v86, v87
	v_cvt_pk_bf16_f32 v71, v66, v67
	v_cvt_pk_bf16_f32 v60, v60, v61
	v_cvt_pk_bf16_f32 v61, v62, v63
	v_cvt_pk_bf16_f32 v62, v56, v57
	v_cvt_pk_bf16_f32 v63, v58, v59
	v_cvt_pk_bf16_f32 v40, v52, v53
	v_cvt_pk_bf16_f32 v41, v54, v55
	v_cvt_pk_bf16_f32 v42, v48, v49
	v_cvt_pk_bf16_f32 v43, v50, v51
	v_cvt_pk_bf16_f32 v24, v36, v37
	v_cvt_pk_bf16_f32 v25, v38, v39
	v_cvt_pk_bf16_f32 v26, v32, v33
	v_cvt_pk_bf16_f32 v27, v34, v35
	global_store_dwordx4 v[28:29], v[12:15], off offset:256 nt
	v_cvt_pk_bf16_f32 v10, v16, v17
	v_cvt_pk_bf16_f32 v11, v18, v19
	v_lshl_add_u64 v[12:13], v[8:9], 0, v[150:151]
	v_cvt_pk_bf16_f32 v8, v20, v21
	v_cvt_pk_bf16_f32 v9, v22, v23
	v_cvt_pk_bf16_f32 v4, v4, v5
	v_cvt_pk_bf16_f32 v5, v6, v7
	v_cvt_pk_bf16_f32 v6, v0, v1
	v_cvt_pk_bf16_f32 v7, v2, v3
	s_and_b64 vcc, exec, s[2:3]
	s_mov_b32 s78, s16
	s_mov_b32 s8, s46
	s_mov_b64 s[54:55], s[50:51]
	s_mov_b64 s[52:53], s[48:49]
	global_store_dwordx4 v[154:155], v[124:127], off nt
	global_store_dwordx4 v[108:109], v[104:107], off nt
	global_store_dwordx4 v[92:93], v[88:91], off nt
	global_store_dwordx4 v[76:77], v[72:75], off nt
	global_store_dwordx4 v[76:77], v[68:71], off offset:256 nt
	global_store_dwordx4 v[64:65], v[60:63], off nt
	global_store_dwordx4 v[44:45], v[40:43], off nt
	global_store_dwordx4 v[28:29], v[24:27], off nt
	global_store_dwordx4 v[12:13], v[8:11], off nt
	global_store_dwordx4 v[12:13], v[4:7], off offset:256 nt
	s_cbranch_vccz .LBB0_110
	s_waitcnt vmcnt(0)
	s_cmpk_gt_u32 s33, 0xff
	s_cbranch_scc1 .LBB0_117
	s_barrier

; #define LAS __attribute__((address_space(3)))
; #define MFMA32(a, b, c) __builtin_amdgcn_mfma_f32_32x32x16_bf16((a), (b), (c), 0, 0, 0)
; DI f32x16 co_qk1(LAS unsigned char* st, const bf16x8 (&qf)[8], int ka_in) {
;     const int ka = ka_in;
;     f32x16 S;
; #pragma unroll
;     for (int i = 0; i < 16; ++i) S[i] = 0.f;
;     __builtin_amdgcn_s_setprio(1);
; #pragma unroll
;     for (int ks = 0; ks < 8; ++ks) { const bf16x8 a = *(const LAS bf16x8*)(st + (ka ^ (32 * ks))); S = MFMA32(a, qf[ks], S); }
;     __builtin_amdgcn_s_setprio(0);
;     return S;
; }
.LBB0_515:
	s_add_i32 s0, s68, 31
	s_cmp_ge_i32 s0, s71
	s_cselect_b64 s[0:1], -1, 0
	s_cmp_le_i32 s68, s72
	s_cselect_b64 s[2:3], -1, 0
	s_and_b64 s[8:9], s[0:1], s[2:3]
	s_and_b32 s16, s76, 0xc000
	v_cndmask_b32_e64 v0, 0, 1, s[8:9]
	v_cmp_ne_u32_e64 s[2:3], 1, v0
	s_andn2_b64 vcc, exec, s[8:9]
	s_add_i32 s16, s16, 0
	s_cbranch_vccnz .LBB0_517
	s_andn2_b64 vcc, exec, s[36:37]
	s_cbranch_vccz .Lfs_win
	s_setprio 1
	v_add_u32_e32 v0, s16, v162
	ds_read_b128 v[2:5], v0
	v_add_u32_e32 v0, s16, v164
	ds_read_b128 v[6:9], v0
	v_add_u32_e32 v0, s16, v165
	s_waitcnt lgkmcnt(0)
	v_mfma_f32_32x32x16_bf16 v[96:111], v[2:5], v[112:115], 0
	ds_read_b128 v[2:5], v0
	v_add_u32_e32 v0, s16, v166
	v_mfma_f32_32x32x16_bf16 v[96:111], v[6:9], v[116:119], v[96:111]
	ds_read_b128 v[6:9], v0
	v_add_u32_e32 v0, s16, v167
	s_waitcnt lgkmcnt(0)
	v_mfma_f32_32x32x16_bf16 v[96:111], v[2:5], v[120:123], v[96:111]
	ds_read_b128 v[2:5], v0
	v_add_u32_e32 v0, s16, v168
	v_mfma_f32_32x32x16_bf16 v[96:111], v[6:9], v[124:127], v[96:111]
	ds_read_b128 v[6:9], v0
	v_add_u32_e32 v0, s16, v169
	s_waitcnt lgkmcnt(0)
	v_mfma_f32_32x32x16_bf16 v[96:111], v[2:5], v[128:131], v[96:111]
	ds_read_b128 v[2:5], v0
	v_add_u32_e32 v0, s16, v170
	v_mfma_f32_32x32x16_bf16 v[96:111], v[6:9], v[132:135], v[96:111]
	ds_read_b128 v[6:9], v0
	s_waitcnt lgkmcnt(0)
	v_mfma_f32_32x32x16_bf16 v[96:111], v[2:5], v[136:139], v[96:111]
	v_mfma_f32_32x32x16_bf16 v[96:111], v[6:9], v[140:143], v[96:111]
	s_setprio 0

; #define LAS __attribute__((address_space(3)))
; #define MFMA32(a, b, c) __builtin_amdgcn_mfma_f32_32x32x16_bf16((a), (b), (c), 0, 0, 0)
; #define CO_STEP2(list, n, i) do { \
;     if ((n) - 1 - (i) >= 1) asm volatile("s_waitcnt vmcnt(2)" ::: "memory"); else asm volatile("s_waitcnt vmcnt(0)" ::: "memory"); \
;     asm volatile("s_waitcnt lgkmcnt(0)" ::: "memory"); __builtin_amdgcn_s_barrier(); asm volatile("" ::: "memory"); \
;     if ((i) + 2 < (n)) co_issue(P, ring, ((i) + 2) & 3, (list)[(i) + 2], b, g, wave, lane); } while (0)
; #define CO_PIPE(MODE, REL, KB, RS) do { const bool rel_ = (REL); LAS unsigned char* sp_ = ring + (i & 3) * 16384; f32x16 Sn_; \
;     if (rel_) Sn_ = co_qk1(sp_, qf, ka); \
;     if (pend) co_finish<MODE>(Sp, pst, pkb, st, tq, prs, vb, hh); \
;     pend = rel_; if (rel_) { Sp = Sn_; pst = sp_; pkb = (KB); prs = (RS); } } while (0)
; DI f32x16 co_qk1(LAS unsigned char* st, const bf16x8 (&qf)[8], int ka_in) {
;     const int ka = ka_in;
;     f32x16 S;
; #pragma unroll
;     for (int i = 0; i < 16; ++i) S[i] = 0.f;
;     __builtin_amdgcn_s_setprio(1);
; #pragma unroll
;     for (int ks = 0; ks < 8; ++ks) { const bf16x8 a = *(const LAS bf16x8*)(st + (ka ^ (32 * ks))); S = MFMA32(a, qf[ks], S); }
;     __builtin_amdgcn_s_setprio(0);
;     return S;
; }
; DI void nsa_block_item(const Params& P, unsigned char* smem_g, int b, int g, int tb, int tid_in) {
;     ...
;     for (i = 0; i < n2; ++i) {
;         CO_STEP2(list2, n2, i); const int kb_ = (int)(list2[i] & 0xffffu); const int j = kb_ >> 6;
;         CO_PIPE(1, ((Uw >> j) & 1u) && kb_ <= t0 + 3, kb_, (bool)((mysel >> j) & 1u));
.LBB0_546:
	v_mov_b32_e32 v0, s71
	ds_read_b32 v0, v0
	s_waitcnt lgkmcnt(0)
	v_readfirstlane_b32 s0, v0
	s_and_b32 s16, s0, 0xffff
	s_bfe_u32 s0, s0, 0xa0006
	s_lshl_b32 s41, 1, s0
	s_and_b32 s0, s41, s70
	s_cmp_lg_u32 s0, 0
	s_cselect_b64 s[0:1], -1, 0
	s_cmp_le_i32 s16, s25
	s_cselect_b64 s[2:3], -1, 0
	s_and_b64 s[8:9], s[0:1], s[2:3]
	s_and_b32 s40, s72, 0xc000
	v_cndmask_b32_e64 v0, 0, 1, s[8:9]
	v_cmp_ne_u32_e64 s[2:3], 1, v0
	s_andn2_b64 vcc, exec, s[8:9]
	s_add_i32 s40, s40, 0
	s_cbranch_vccnz .LBB0_548
	s_andn2_b64 vcc, exec, s[36:37]
	s_cbranch_vccz .Lfs_sel
	s_setprio 1
	v_add_u32_e32 v0, s40, v162
	ds_read_b128 v[2:5], v0
	v_add_u32_e32 v0, s40, v164
	ds_read_b128 v[6:9], v0
	v_add_u32_e32 v0, s40, v165
	s_waitcnt lgkmcnt(0)
	v_mfma_f32_32x32x16_bf16 v[96:111], v[2:5], v[112:115], 0
	ds_read_b128 v[2:5], v0
	v_add_u32_e32 v0, s40, v166
	v_mfma_f32_32x32x16_bf16 v[96:111], v[6:9], v[116:119], v[96:111]
	ds_read_b128 v[6:9], v0
	v_add_u32_e32 v0, s40, v167
	s_waitcnt lgkmcnt(0)
	v_mfma_f32_32x32x16_bf16 v[96:111], v[2:5], v[120:123], v[96:111]
	ds_read_b128 v[2:5], v0
	v_add_u32_e32 v0, s40, v168
	v_mfma_f32_32x32x16_bf16 v[96:111], v[6:9], v[124:127], v[96:111]
	ds_read_b128 v[6:9], v0
	v_add_u32_e32 v0, s40, v169
	s_waitcnt lgkmcnt(0)
	v_mfma_f32_32x32x16_bf16 v[96:111], v[2:5], v[128:131], v[96:111]
	ds_read_b128 v[2:5], v0
	v_add_u32_e32 v0, s40, v170
	v_mfma_f32_32x32x16_bf16 v[96:111], v[6:9], v[132:135], v[96:111]
	ds_read_b128 v[6:9], v0
	s_waitcnt lgkmcnt(0)
	v_mfma_f32_32x32x16_bf16 v[96:111], v[2:5], v[136:139], v[96:111]
	v_mfma_f32_32x32x16_bf16 v[96:111], v[6:9], v[140:143], v[96:111]
	s_setprio 0

; #define LAS __attribute__((address_space(3)))
; DI float xh_max(float x) { const unsigned u = __float_as_uint(x); const auto r = __builtin_amdgcn_permlane32_swap(u, u, false, false); return fmaxf(__uint_as_float(r[0]), __uint_as_float(r[1])); }
; DI float xh_sum(float x) { const unsigned u = __float_as_uint(x); const auto r = __builtin_amdgcn_permlane32_swap(u, u, false, false); return __uint_as_float(r[0]) + __uint_as_float(r[1]); }
; #define MFMA32(a, b, c) __builtin_amdgcn_mfma_f32_32x32x16_bf16((a), (b), (c), 0, 0, 0)
; DI f32x16 co_qk1(LAS unsigned char* st, const bf16x8 (&qf)[8], int ka_in) {
;     const int ka = ka_in;
;     f32x16 S;
; #pragma unroll
;     for (int i = 0; i < 16; ++i) S[i] = 0.f;
;     __builtin_amdgcn_s_setprio(1);
; #pragma unroll
;     for (int ks = 0; ks < 8; ++ks) { const bf16x8 a = *(const LAS bf16x8*)(st + (ka ^ (32 * ks))); S = MFMA32(a, qf[ks], S); }
;     __builtin_amdgcn_s_setprio(0);
;     return S;
; }
; template <int MODE>
; DI void co_finish(f32x16 S, LAS unsigned char* st, int key_base, AttnState& as, int tq, bool rowsel, int vb_in, int hh) {
;     const int vb = vb_in;
;     {
;         const int base = key_base + 4 * hh;
;         const int hi = (MODE == 0) ? (((tq - 31) >> 4) - base) : (tq - base);
;         const int lo = hi - 512;
; #pragma unroll
;         for (int i = 0; i < 16; ++i) { const int c = (i & 3) + 8 * (i >> 2); bool ok = (c <= hi); if (MODE == 2) ok = ok && (c > lo); if (MODE == 1) ok = ok && rowsel; S[i] = ok ? S[i] : -1e30f; }
;     }
;     float mx = S[0];
; #pragma unroll
;     for (int i = 1; i < 16; ++i) mx = fmaxf(mx, S[i]);
;     mx = xh_max(mx);
;     const float mxs = mx * SM_SCALE; const bool need = mxs > as.m + 8.f;
;     const float mnew = need ? mxs : as.m, muse = -fmaxf(mnew, -1e20f); float ps = 0.f;
; #pragma unroll
;     for (int i = 0; i < 16; ++i) { const float p = __builtin_amdgcn_exp2f(__builtin_fmaf(S[i], SM_SCALE, muse)); S[i] = p; ps += p; }
;     ps = xh_sum(ps);
;     if (__builtin_amdgcn_ballot_w64(need) != 0ull) {
.Lfs_sel:
	v_add_u32_e32 v246, s40, v162
	ds_read_b128 v[238:241], v246
	v_add_u32_e32 v246, s40, v164
	ds_read_b128 v[242:245], v246
	v_add_u32_e32 v0, s74, v145
	v_cmp_lt_i32_e32 vcc, -1, v0
	s_and_b64 vcc, s[26:27], vcc
	s_nop 0
	v_cndmask_b32_e32 v2, v153, v16, vcc
	v_cmp_lt_i32_e32 vcc, 0, v0
	s_and_b64 vcc, s[26:27], vcc
	v_max_f32_e32 v174, v2, v2
	v_cndmask_b32_e32 v3, v153, v17, vcc
	v_cmp_lt_i32_e32 vcc, 1, v0
	s_and_b64 vcc, s[26:27], vcc
	s_nop 0
	v_cndmask_b32_e32 v4, v153, v18, vcc
	s_waitcnt lgkmcnt(1)
	v_mfma_f32_32x32x16_bf16 v[96:111], v[238:241], v[112:115], 0
	v_add_u32_e32 v246, s40, v165
	ds_read_b128 v[238:241], v246
	v_cmp_lt_i32_e32 vcc, 2, v0
	s_and_b64 vcc, s[26:27], vcc
	s_nop 0
	v_cndmask_b32_e32 v5, v153, v19, vcc
	v_cmp_lt_i32_e32 vcc, 7, v0
	s_and_b64 vcc, s[26:27], vcc
	s_nop 0
	v_cndmask_b32_e32 v6, v153, v20, vcc
	v_cmp_lt_i32_e32 vcc, 8, v0
	s_and_b64 vcc, s[26:27], vcc
	s_nop 0
	v_cndmask_b32_e32 v7, v153, v21, vcc
	v_cmp_lt_i32_e32 vcc, 9, v0
	s_and_b64 vcc, s[26:27], vcc
	s_waitcnt lgkmcnt(1)
	v_mfma_f32_32x32x16_bf16 v[96:111], v[242:245], v[116:119], v[96:111]
	v_add_u32_e32 v246, s40, v166
	ds_read_b128 v[242:245], v246
	s_nop 0
	v_cndmask_b32_e32 v8, v153, v22, vcc
	v_cmp_lt_i32_e32 vcc, 10, v0
	s_and_b64 vcc, s[26:27], vcc
	s_nop 0
	v_cndmask_b32_e32 v9, v153, v23, vcc
	v_cmp_lt_i32_e32 vcc, 15, v0
	s_and_b64 vcc, s[26:27], vcc
	s_nop 0
	v_cndmask_b32_e32 v10, v153, v24, vcc
	v_cmp_lt_i32_e32 vcc, 16, v0
	s_and_b64 vcc, s[26:27], vcc
	s_nop 0
	v_cndmask_b32_e32 v11, v153, v25, vcc
	s_waitcnt lgkmcnt(1)
	v_mfma_f32_32x32x16_bf16 v[96:111], v[238:241], v[120:123], v[96:111]
	v_add_u32_e32 v246, s40, v167
	ds_read_b128 v[238:241], v246
	v_cmp_lt_i32_e32 vcc, 17, v0
	s_and_b64 vcc, s[26:27], vcc
	s_nop 0
	v_cndmask_b32_e32 v12, v153, v26, vcc
	v_cmp_lt_i32_e32 vcc, 18, v0
	s_and_b64 vcc, s[26:27], vcc
	s_nop 0
	v_cndmask_b32_e32 v13, v153, v27, vcc
	v_cmp_lt_i32_e32 vcc, 23, v0
	s_and_b64 vcc, s[26:27], vcc
	s_nop 0
	v_cndmask_b32_e32 v14, v153, v28, vcc
	v_cmp_lt_i32_e32 vcc, 24, v0
	s_waitcnt lgkmcnt(1)
	v_mfma_f32_32x32x16_bf16 v[96:111], v[242:245], v[124:127], v[96:111]
	v_add_u32_e32 v246, s40, v168
	ds_read_b128 v[242:245], v246
	s_and_b64 vcc, s[26:27], vcc
	s_nop 0
	v_cndmask_b32_e32 v15, v153, v29, vcc
	v_cmp_lt_i32_e32 vcc, 25, v0
	s_and_b64 vcc, s[26:27], vcc
	s_nop 0
	v_cndmask_b32_e32 v176, v153, v30, vcc
	v_cmp_lt_i32_e32 vcc, 26, v0
	v_max_f32_e32 v0, v3, v3
	v_max_f32_e32 v0, v174, v0
	v_max3_f32 v0, v0, v4, v5
	v_max3_f32 v0, v0, v6, v7
	v_max3_f32 v0, v0, v8, v9
	v_max3_f32 v0, v0, v10, v11
	s_waitcnt lgkmcnt(1)
	v_mfma_f32_32x32x16_bf16 v[96:111], v[238:241], v[128:131], v[96:111]
	v_add_u32_e32 v246, s40, v169
	ds_read_b128 v[238:241], v246
	s_and_b64 vcc, s[26:27], vcc
	v_max3_f32 v0, v0, v12, v13
	v_cndmask_b32_e32 v177, v153, v31, vcc
	v_max3_f32 v0, v0, v14, v15
	v_max3_f32 v0, v0, v176, v177
	v_mov_b32_e32 v174, v0
	s_nop 1
	v_permlane32_swap_b32_e32 v0, v174
	v_max_f32_e32 v174, v174, v174
	v_max_f32_e32 v0, v0, v0
	v_max_f32_e32 v0, v0, v174
	v_mul_f32_e32 v0, 0x3e0293ee, v0
	v_add_f32_e32 v174, 0x41000000, v175
	v_cmp_gt_f32_e32 vcc, v0, v174
	s_waitcnt lgkmcnt(1)
	v_mfma_f32_32x32x16_bf16 v[96:111], v[242:245], v[132:135], v[96:111]
	v_add_u32_e32 v246, s40, v170
	ds_read_b128 v[242:245], v246
	s_nop 1
	v_cndmask_b32_e32 v174, v175, v0, vcc
	v_max_f32_e32 v0, v174, v174
	v_max_f32_e32 v178, 0xe0ad78ec, v0
	v_fma_f32 v0, v2, s52, -v178
	v_exp_f32_e32 v0, v0
	v_fma_f32 v2, v3, s52, -v178
	v_exp_f32_e32 v2, v2
	v_fma_f32 v3, v4, s52, -v178
	v_exp_f32_e32 v3, v3
	v_fma_f32 v4, v5, s52, -v178
	v_exp_f32_e32 v4, v4
	v_add_f32_e32 v5, 0, v0
	s_waitcnt lgkmcnt(1)
	v_mfma_f32_32x32x16_bf16 v[96:111], v[238:241], v[136:139], v[96:111]
	v_add_f32_e32 v5, v2, v5
	v_add_f32_e32 v5, v3, v5
	v_add_f32_e32 v179, v4, v5
	v_fma_f32 v5, v6, s52, -v178
	v_exp_f32_e32 v5, v5
	v_fma_f32 v6, v7, s52, -v178
	v_exp_f32_e32 v6, v6
	v_fma_f32 v7, v8, s52, -v178
	v_exp_f32_e32 v7, v7
	v_fma_f32 v8, v9, s52, -v178
	v_exp_f32_e32 v8, v8
	v_add_f32_e32 v9, v5, v179
	v_add_f32_e32 v9, v6, v9
	v_add_f32_e32 v9, v7, v9
	s_waitcnt lgkmcnt(0)
	v_mfma_f32_32x32x16_bf16 v[96:111], v[242:245], v[140:143], v[96:111]
	v_add_f32_e32 v179, v8, v9
	v_fma_f32 v9, v10, s52, -v178
	v_exp_f32_e32 v9, v9
	v_fma_f32 v10, v11, s52, -v178
	v_exp_f32_e32 v10, v10
	v_fma_f32 v11, v12, s52, -v178
	v_exp_f32_e32 v11, v11
	v_fma_f32 v12, v13, s52, -v178
	v_exp_f32_e32 v12, v12
	v_add_f32_e32 v13, v9, v179
	v_add_f32_e32 v13, v10, v13
	v_add_f32_e32 v13, v11, v13
	v_add_f32_e32 v179, v12, v13
	v_fma_f32 v13, v14, s52, -v178
	v_exp_f32_e32 v13, v13
	v_fma_f32 v14, v15, s52, -v178
	v_exp_f32_e32 v14, v14
	v_fma_f32 v15, v176, s52, -v178
	v_exp_f32_e32 v15, v15
	v_fma_f32 v176, v177, s52, -v178
	v_exp_f32_e32 v176, v176
	v_add_f32_e32 v177, v13, v179
	v_add_f32_e32 v177, v14, v177
	v_add_f32_e32 v177, v15, v177
	v_add_f32_e32 v177, v176, v177
	v_mov_b32_e32 v178, v177
	s_nop 1
	v_permlane32_swap_b32_e32 v177, v178
	s_cbranch_vccz .Lfs_sel_551
; template <int MODE>
; DI void co_finish(f32x16 S, LAS unsigned char* st, int key_base, AttnState& as, int tq, bool rowsel, int vb_in, int hh) {
;     ...
;     if (__builtin_amdgcn_ballot_w64(need) != 0ull) {
;         const float alpha = __builtin_amdgcn_exp2f(as.m - mnew);
;         as.l *= alpha;
; #pragma unroll
;         for (int dt = 0; dt < 4; ++dt)
; #pragma unroll
;             for (int i = 0; i < 16; ++i) as.acc[dt][i] *= alpha;
;     }
	v_sub_f32_e32 v175, v175, v174
	v_exp_f32_e32 v180, v175
	s_nop 0
	v_mul_f32_e32 v163, v163, v180
	v_pk_mul_f32 v[94:95], v[94:95], v[180:181] op_sel_hi:[1,0]
	v_pk_mul_f32 v[92:93], v[92:93], v[180:181] op_sel_hi:[1,0]
	v_pk_mul_f32 v[90:91], v[90:91], v[180:181] op_sel_hi:[1,0]
	v_pk_mul_f32 v[88:89], v[88:89], v[180:181] op_sel_hi:[1,0]
	v_pk_mul_f32 v[86:87], v[86:87], v[180:181] op_sel_hi:[1,0]
	v_pk_mul_f32 v[84:85], v[84:85], v[180:181] op_sel_hi:[1,0]
	v_pk_mul_f32 v[82:83], v[82:83], v[180:181] op_sel_hi:[1,0]
	v_pk_mul_f32 v[80:81], v[80:81], v[180:181] op_sel_hi:[1,0]
	v_pk_mul_f32 v[78:79], v[78:79], v[180:181] op_sel_hi:[1,0]
	v_pk_mul_f32 v[76:77], v[76:77], v[180:181] op_sel_hi:[1,0]
	v_pk_mul_f32 v[74:75], v[74:75], v[180:181] op_sel_hi:[1,0]
	v_pk_mul_f32 v[72:73], v[72:73], v[180:181] op_sel_hi:[1,0]
	v_pk_mul_f32 v[70:71], v[70:71], v[180:181] op_sel_hi:[1,0]
	v_pk_mul_f32 v[68:69], v[68:69], v[180:181] op_sel_hi:[1,0]
	v_pk_mul_f32 v[66:67], v[66:67], v[180:181] op_sel_hi:[1,0]
	v_pk_mul_f32 v[64:65], v[64:65], v[180:181] op_sel_hi:[1,0]
	v_pk_mul_f32 v[62:63], v[62:63], v[180:181] op_sel_hi:[1,0]
	v_pk_mul_f32 v[60:61], v[60:61], v[180:181] op_sel_hi:[1,0]
	v_pk_mul_f32 v[58:59], v[58:59], v[180:181] op_sel_hi:[1,0]
	v_pk_mul_f32 v[56:57], v[56:57], v[180:181] op_sel_hi:[1,0]
	v_pk_mul_f32 v[54:55], v[54:55], v[180:181] op_sel_hi:[1,0]
	v_pk_mul_f32 v[52:53], v[52:53], v[180:181] op_sel_hi:[1,0]
	v_pk_mul_f32 v[50:51], v[50:51], v[180:181] op_sel_hi:[1,0]
	v_pk_mul_f32 v[48:49], v[48:49], v[180:181] op_sel_hi:[1,0]
	v_pk_mul_f32 v[46:47], v[46:47], v[180:181] op_sel_hi:[1,0]
	v_pk_mul_f32 v[44:45], v[44:45], v[180:181] op_sel_hi:[1,0]
	v_pk_mul_f32 v[42:43], v[42:43], v[180:181] op_sel_hi:[1,0]
	v_pk_mul_f32 v[40:41], v[40:41], v[180:181] op_sel_hi:[1,0]
	v_pk_mul_f32 v[38:39], v[38:39], v[180:181] op_sel_hi:[1,0]
	v_pk_mul_f32 v[36:37], v[36:37], v[180:181] op_sel_hi:[1,0]
	v_pk_mul_f32 v[34:35], v[34:35], v[180:181] op_sel_hi:[1,0]
	v_pk_mul_f32 v[32:33], v[32:33], v[180:181] op_sel_hi:[1,0]

; #define LAS __attribute__((address_space(3)))
; DI float xh_max(float x) { const unsigned u = __float_as_uint(x); const auto r = __builtin_amdgcn_permlane32_swap(u, u, false, false); return fmaxf(__uint_as_float(r[0]), __uint_as_float(r[1])); }
; DI float xh_sum(float x) { const unsigned u = __float_as_uint(x); const auto r = __builtin_amdgcn_permlane32_swap(u, u, false, false); return __uint_as_float(r[0]) + __uint_as_float(r[1]); }
; template <int MODE>
; DI void co_finish(f32x16 S, LAS unsigned char* st, int key_base, AttnState& as, int tq, bool rowsel, int vb_in, int hh) {
;     const int vb = vb_in;
;     {
;         const int base = key_base + 4 * hh;
;         const int hi = (MODE == 0) ? (((tq - 31) >> 4) - base) : (tq - base);
;         const int lo = hi - 512;
; #pragma unroll
;         for (int i = 0; i < 16; ++i) { const int c = (i & 3) + 8 * (i >> 2); bool ok = (c <= hi); if (MODE == 2) ok = ok && (c > lo); if (MODE == 1) ok = ok && rowsel; S[i] = ok ? S[i] : -1e30f; }
;     }
;     float mx = S[0];
; #pragma unroll
;     for (int i = 1; i < 16; ++i) mx = fmaxf(mx, S[i]);
;     mx = xh_max(mx);
;     const float mxs = mx * SM_SCALE; const bool need = mxs > as.m + 8.f;
;     const float mnew = need ? mxs : as.m, muse = -fmaxf(mnew, -1e20f); float ps = 0.f;
; #pragma unroll
;     for (int i = 0; i < 16; ++i) { const float p = __builtin_amdgcn_exp2f(__builtin_fmaf(S[i], SM_SCALE, muse)); S[i] = p; ps += p; }
;     ps = xh_sum(ps);
;     if (__builtin_amdgcn_ballot_w64(need) != 0ull) {
;         const float alpha = __builtin_amdgcn_exp2f(as.m - mnew);
;         as.l *= alpha;
; #pragma unroll
;         for (int dt = 0; dt < 4; ++dt)
; #pragma unroll
;             for (int i = 0; i < 16; ++i) as.acc[dt][i] *= alpha;
;     }
.Lfs_win:
	v_add_u32_e32 v246, s16, v162
	ds_read_b128 v[238:241], v246
	v_add_u32_e32 v246, s16, v164
	ds_read_b128 v[242:245], v246
	v_add_u32_e32 v0, s79, v145
	v_cmp_gt_u32_e32 vcc, s53, v0
	v_add_u32_e32 v3, -1, v0
	v_add_u32_e32 v4, -2, v0
	v_cndmask_b32_e32 v2, v153, v16, vcc
	v_cmp_gt_u32_e32 vcc, s53, v3
	v_add_u32_e32 v5, -3, v0
	v_add_u32_e32 v6, -8, v0
	v_cndmask_b32_e32 v3, v153, v17, vcc
	v_cmp_gt_u32_e32 vcc, s53, v4
	v_add_u32_e32 v7, -9, v0
	v_add_u32_e32 v8, -10, v0
	v_cndmask_b32_e32 v4, v153, v18, vcc
	s_waitcnt lgkmcnt(1)
	v_mfma_f32_32x32x16_bf16 v[96:111], v[238:241], v[112:115], 0
	v_add_u32_e32 v246, s16, v165
	ds_read_b128 v[238:241], v246
	v_cmp_gt_u32_e32 vcc, s53, v5
	v_add_u32_e32 v9, -11, v0
	v_add_u32_e32 v10, -16, v0
	v_cndmask_b32_e32 v5, v153, v19, vcc
	v_cmp_gt_u32_e32 vcc, s53, v6
	v_subrev_u32_e32 v11, 17, v0
	v_subrev_u32_e32 v12, 18, v0
	v_cndmask_b32_e32 v6, v153, v20, vcc
	v_cmp_gt_u32_e32 vcc, s53, v7
	v_subrev_u32_e32 v13, 19, v0
	v_subrev_u32_e32 v14, 24, v0
	v_cndmask_b32_e32 v7, v153, v21, vcc
	v_cmp_gt_u32_e32 vcc, s53, v8
	s_waitcnt lgkmcnt(1)
	v_mfma_f32_32x32x16_bf16 v[96:111], v[242:245], v[116:119], v[96:111]
	v_add_u32_e32 v246, s16, v166
	ds_read_b128 v[242:245], v246
	v_subrev_u32_e32 v15, 25, v0
	v_subrev_u32_e32 v176, 26, v0
	v_cndmask_b32_e32 v8, v153, v22, vcc
	v_cmp_gt_u32_e32 vcc, s53, v9
	v_subrev_u32_e32 v0, 27, v0
	s_nop 0
	v_cndmask_b32_e32 v9, v153, v23, vcc
	v_cmp_gt_u32_e32 vcc, s53, v10
	s_nop 1
	v_cndmask_b32_e32 v10, v153, v24, vcc
	v_cmp_gt_u32_e32 vcc, s53, v11
	s_nop 1
	v_cndmask_b32_e32 v11, v153, v25, vcc
	s_waitcnt lgkmcnt(1)
	v_mfma_f32_32x32x16_bf16 v[96:111], v[238:241], v[120:123], v[96:111]
	v_add_u32_e32 v246, s16, v167
	ds_read_b128 v[238:241], v246
	v_cmp_gt_u32_e32 vcc, s53, v12
	s_nop 1
	v_cndmask_b32_e32 v12, v153, v26, vcc
	v_cmp_gt_u32_e32 vcc, s53, v13
	s_nop 1
	v_cndmask_b32_e32 v13, v153, v27, vcc
	v_cmp_gt_u32_e32 vcc, s53, v14
	s_nop 1
	v_cndmask_b32_e32 v14, v153, v28, vcc
	v_cmp_gt_u32_e32 vcc, s53, v15
	s_nop 1
	v_cndmask_b32_e32 v15, v153, v29, vcc
	v_cmp_gt_u32_e32 vcc, s53, v176
	s_waitcnt lgkmcnt(1)
	v_mfma_f32_32x32x16_bf16 v[96:111], v[242:245], v[124:127], v[96:111]
	v_add_u32_e32 v246, s16, v168
	ds_read_b128 v[242:245], v246
	v_max_f32_e32 v176, v3, v3
	s_nop 0
	v_cndmask_b32_e32 v178, v153, v30, vcc
	v_cmp_gt_u32_e32 vcc, s53, v0
	v_max_f32_e32 v0, v2, v2
	v_max_f32_e32 v0, v0, v176
	v_max3_f32 v0, v0, v4, v5
	v_max3_f32 v0, v0, v6, v7
	v_max3_f32 v0, v0, v8, v9
	v_max3_f32 v0, v0, v10, v11
	v_max3_f32 v0, v0, v12, v13
	v_cndmask_b32_e32 v179, v153, v31, vcc
	v_max3_f32 v0, v0, v14, v15
	s_waitcnt lgkmcnt(1)
	v_mfma_f32_32x32x16_bf16 v[96:111], v[238:241], v[128:131], v[96:111]
	v_add_u32_e32 v246, s16, v169
	ds_read_b128 v[238:241], v246
	v_max3_f32 v0, v0, v178, v179
	v_mov_b32_e32 v176, v0
	s_nop 1
	v_permlane32_swap_b32_e32 v0, v176
	v_max_f32_e32 v176, v176, v176
	v_max_f32_e32 v0, v0, v0
	v_max_f32_e32 v0, v0, v176
	v_mul_f32_e32 v0, 0x3e0293ee, v0
	v_add_f32_e32 v176, 0x41000000, v177
	v_cmp_gt_f32_e32 vcc, v0, v176
	s_nop 1
	v_cndmask_b32_e32 v176, v177, v0, vcc
	v_max_f32_e32 v0, v176, v176
	s_waitcnt lgkmcnt(1)
	v_mfma_f32_32x32x16_bf16 v[96:111], v[242:245], v[132:135], v[96:111]
	v_add_u32_e32 v246, s16, v170
	ds_read_b128 v[242:245], v246
	v_max_f32_e32 v180, 0xe0ad78ec, v0
	v_fma_f32 v0, v2, s52, -v180
	v_exp_f32_e32 v0, v0
	v_fma_f32 v2, v3, s52, -v180
	v_exp_f32_e32 v2, v2
	v_fma_f32 v3, v4, s52, -v180
	v_exp_f32_e32 v3, v3
	v_fma_f32 v4, v5, s52, -v180
	v_exp_f32_e32 v4, v4
	v_add_f32_e32 v5, 0, v0
	v_add_f32_e32 v5, v2, v5
	v_add_f32_e32 v5, v3, v5
	v_add_f32_e32 v181, v4, v5
	s_waitcnt lgkmcnt(1)
	v_mfma_f32_32x32x16_bf16 v[96:111], v[238:241], v[136:139], v[96:111]
	v_fma_f32 v5, v6, s52, -v180
	v_exp_f32_e32 v5, v5
	v_fma_f32 v6, v7, s52, -v180
	v_exp_f32_e32 v6, v6
	v_fma_f32 v7, v8, s52, -v180
	v_exp_f32_e32 v7, v7
	v_fma_f32 v8, v9, s52, -v180
	v_exp_f32_e32 v8, v8
	v_add_f32_e32 v9, v5, v181
	v_add_f32_e32 v9, v6, v9
	v_add_f32_e32 v9, v7, v9
	v_add_f32_e32 v181, v8, v9
	v_fma_f32 v9, v10, s52, -v180
	s_waitcnt lgkmcnt(0)
	v_mfma_f32_32x32x16_bf16 v[96:111], v[242:245], v[140:143], v[96:111]
	v_exp_f32_e32 v9, v9
	v_fma_f32 v10, v11, s52, -v180
	v_exp_f32_e32 v10, v10
	v_fma_f32 v11, v12, s52, -v180
	v_exp_f32_e32 v11, v11
	v_fma_f32 v12, v13, s52, -v180
	v_exp_f32_e32 v12, v12
	v_add_f32_e32 v13, v9, v181
	v_add_f32_e32 v13, v10, v13
	v_add_f32_e32 v13, v11, v13
	v_add_f32_e32 v181, v12, v13
	v_fma_f32 v13, v14, s52, -v180
	v_exp_f32_e32 v13, v13
	v_fma_f32 v14, v15, s52, -v180
	v_exp_f32_e32 v14, v14
	v_fma_f32 v15, v178, s52, -v180
	v_exp_f32_e32 v15, v15
	v_fma_f32 v178, v179, s52, -v180
	v_exp_f32_e32 v178, v178
	v_add_f32_e32 v179, v13, v181
	v_add_f32_e32 v179, v14, v179
	v_add_f32_e32 v179, v15, v179
	v_add_f32_e32 v179, v178, v179
	v_mov_b32_e32 v180, v179
	s_nop 1
	v_permlane32_swap_b32_e32 v179, v180
	s_cbranch_vccz .Lfs_win_520
	v_sub_f32_e32 v177, v177, v176
	v_exp_f32_e32 v182, v177
	s_nop 0
	v_mul_f32_e32 v175, v175, v182
	v_pk_mul_f32 v[94:95], v[94:95], v[182:183] op_sel_hi:[1,0]
	v_pk_mul_f32 v[92:93], v[92:93], v[182:183] op_sel_hi:[1,0]
	v_pk_mul_f32 v[90:91], v[90:91], v[182:183] op_sel_hi:[1,0]
	v_pk_mul_f32 v[88:89], v[88:89], v[182:183] op_sel_hi:[1,0]
	v_pk_mul_f32 v[86:87], v[86:87], v[182:183] op_sel_hi:[1,0]
	v_pk_mul_f32 v[84:85], v[84:85], v[182:183] op_sel_hi:[1,0]
	v_pk_mul_f32 v[82:83], v[82:83], v[182:183] op_sel_hi:[1,0]
	v_pk_mul_f32 v[80:81], v[80:81], v[182:183] op_sel_hi:[1,0]
	v_pk_mul_f32 v[78:79], v[78:79], v[182:183] op_sel_hi:[1,0]
	v_pk_mul_f32 v[76:77], v[76:77], v[182:183] op_sel_hi:[1,0]
	v_pk_mul_f32 v[74:75], v[74:75], v[182:183] op_sel_hi:[1,0]
	v_pk_mul_f32 v[72:73], v[72:73], v[182:183] op_sel_hi:[1,0]
	v_pk_mul_f32 v[70:71], v[70:71], v[182:183] op_sel_hi:[1,0]
	v_pk_mul_f32 v[68:69], v[68:69], v[182:183] op_sel_hi:[1,0]
	v_pk_mul_f32 v[66:67], v[66:67], v[182:183] op_sel_hi:[1,0]
	v_pk_mul_f32 v[64:65], v[64:65], v[182:183] op_sel_hi:[1,0]
	v_pk_mul_f32 v[62:63], v[62:63], v[182:183] op_sel_hi:[1,0]
	v_pk_mul_f32 v[60:61], v[60:61], v[182:183] op_sel_hi:[1,0]
	v_pk_mul_f32 v[58:59], v[58:59], v[182:183] op_sel_hi:[1,0]
	v_pk_mul_f32 v[56:57], v[56:57], v[182:183] op_sel_hi:[1,0]
	v_pk_mul_f32 v[54:55], v[54:55], v[182:183] op_sel_hi:[1,0]
	v_pk_mul_f32 v[52:53], v[52:53], v[182:183] op_sel_hi:[1,0]
	v_pk_mul_f32 v[50:51], v[50:51], v[182:183] op_sel_hi:[1,0]
	v_pk_mul_f32 v[48:49], v[48:49], v[182:183] op_sel_hi:[1,0]
	v_pk_mul_f32 v[46:47], v[46:47], v[182:183] op_sel_hi:[1,0]
	v_pk_mul_f32 v[44:45], v[44:45], v[182:183] op_sel_hi:[1,0]
	v_pk_mul_f32 v[42:43], v[42:43], v[182:183] op_sel_hi:[1,0]
	v_pk_mul_f32 v[40:41], v[40:41], v[182:183] op_sel_hi:[1,0]
	v_pk_mul_f32 v[38:39], v[38:39], v[182:183] op_sel_hi:[1,0]
	v_pk_mul_f32 v[36:37], v[36:37], v[182:183] op_sel_hi:[1,0]
	v_pk_mul_f32 v[34:35], v[34:35], v[182:183] op_sel_hi:[1,0]
	v_pk_mul_f32 v[32:33], v[32:33], v[182:183] op_sel_hi:[1,0]
; #define LAS __attribute__((address_space(3)))
; #define MFMA32(a, b, c) __builtin_amdgcn_mfma_f32_32x32x16_bf16((a), (b), (c), 0, 0, 0)
; DI bf16x8 cat44(s16x4 a, s16x4 b) { return __builtin_shufflevector(a, b, 0, 1, 2, 3, 4, 5, 6, 7); }
; template <int MODE>
; DI void co_finish(f32x16 S, LAS unsigned char* st, int key_base, AttnState& as, int tq, bool rowsel, int vb_in, int hh) {
;     ...
;     as.l += ps; as.m = mnew;
;     const bf16x8 p0 = pack8(S, 0), p1 = pack8(S, 1);
;     __builtin_amdgcn_s_setprio(1);
; #pragma unroll
;     for (int dt = 0; dt < 4; ++dt) {
;         LAS unsigned char* vp = st + 2048 * dt;
;         const bf16x8 a0 = cat44(*(const LAS s16x4*)(vp + (vb ^ 0)), *(const LAS s16x4*)(vp + (vb ^ 16))), a1 = cat44(*(const LAS s16x4*)(vp + (vb ^ 32)), *(const LAS s16x4*)(vp + (vb ^ 48)));
;         as.acc[dt] = MFMA32(a0, p0, as.acc[dt]); as.acc[dt] = MFMA32(a1, p1, as.acc[dt]);
;     }
; DI void xcd_barrier(const XcdBarrier& b) {
;     asm volatile("s_waitcnt vmcnt(0)" ::: "memory");
;     __syncthreads();
;     if (threadIdx.x == 0) {
;         unsigned* bar = b.bar;
;         __builtin_amdgcn_s_waitcnt(0);
;         unsigned nloc = b.st[0], nx = b.st[1];
;         if (nloc == 0u) { xcd_barrier_complete(bar, b.x, nloc, nx); b.st[0] = nloc; b.st[1] = nx; }
.Lfs_win_520:
	v_add_f32_e32 v177, v179, v180
	v_add_f32_e32 v175, v177, v175
	v_cvt_pk_bf16_f32 v2, v0, v2
	v_cvt_pk_bf16_f32 v3, v3, v4
	v_cvt_pk_bf16_f32 v4, v5, v6
	v_cvt_pk_bf16_f32 v5, v7, v8
	v_cvt_pk_bf16_f32 v6, v9, v10
	v_cvt_pk_bf16_f32 v7, v11, v12
	v_cvt_pk_bf16_f32 v8, v13, v14
	v_cvt_pk_bf16_f32 v9, v15, v178
	s_setprio 1
	v_add_u32_e32 v0, s62, v156
	v_add_u32_e32 v14, s62, v171
	ds_read2st64_b64 v[10:13], v0 offset0:16 offset1:20
	ds_read2st64_b64 v[178:181], v14 offset0:16 offset1:20
	v_add_u32_e32 v15, s62, v172
	v_add_u32_e32 v177, s62, v173
	ds_read2st64_b64 v[186:189], v15 offset0:16 offset1:20
	ds_read2st64_b64 v[190:193], v177 offset0:16 offset1:20
	s_waitcnt lgkmcnt(0)
	v_mov_b32_e32 v184, v178
	v_mov_b32_e32 v185, v179
	v_mov_b32_e32 v178, v12
	v_mov_b32_e32 v179, v13
	v_mov_b32_e32 v182, v10
	v_mov_b32_e32 v183, v11
	v_mfma_f32_32x32x16_bf16 v[64:79], v[178:181], v[2:5], v[64:79]
	ds_read2st64_b64 v[10:13], v0 offset0:24 offset1:28
	ds_read2st64_b64 v[178:181], v14 offset0:24 offset1:28
	v_mov_b32_e32 v196, v190
	v_mov_b32_e32 v197, v191
	v_mov_b32_e32 v190, v188
	v_mov_b32_e32 v191, v189
	v_mov_b32_e32 v194, v186
	v_mov_b32_e32 v195, v187
	v_mfma_f32_32x32x16_bf16 v[80:95], v[182:185], v[2:5], v[80:95]
	s_waitcnt lgkmcnt(0)
	v_mov_b32_e32 v182, v10
	v_mov_b32_e32 v183, v11
	v_mov_b32_e32 v184, v178
	v_mov_b32_e32 v185, v179
	v_mov_b32_e32 v178, v12
	v_mov_b32_e32 v179, v13
	ds_read2st64_b64 v[186:189], v15 offset0:24 offset1:28
	v_mfma_f32_32x32x16_bf16 v[64:79], v[190:193], v[6:9], v[64:79]
	ds_read2st64_b64 v[190:193], v177 offset0:24 offset1:28
	v_mfma_f32_32x32x16_bf16 v[48:63], v[182:185], v[2:5], v[48:63]
	v_mfma_f32_32x32x16_bf16 v[32:47], v[178:181], v[2:5], v[32:47]
	v_mfma_f32_32x32x16_bf16 v[80:95], v[194:197], v[6:9], v[80:95]
	s_waitcnt lgkmcnt(0)
	v_mov_b32_e32 v194, v186
	v_mov_b32_e32 v195, v187
	v_mov_b32_e32 v196, v190
	v_mov_b32_e32 v197, v191
	v_mov_b32_e32 v190, v188
	v_mov_b32_e32 v191, v189
	v_mfma_f32_32x32x16_bf16 v[48:63], v[194:197], v[6:9], v[48:63]
	s_nop 0
	v_mfma_f32_32x32x16_bf16 v[32:47], v[190:193], v[6:9], v[32:47]
	s_setprio 0
	s_and_b64 vcc, exec, s[2:3]
	s_cbranch_vccz .LBB0_522
	s_branch .LBB0_523
.LBB0_562:
	s_waitcnt vmcnt(0)
	s_barrier
	s_mov_b64 s[2:3], exec
	v_readlane_b32 s0, v236, 0
	v_readlane_b32 s1, v236, 1
	s_and_b64 s[0:1], s[2:3], s[0:1]
	s_mov_b64 exec, s[0:1]
	s_cbranch_execz .LBB0_614
	s_add_i32 s0, 0, 0x27ff0
	v_mov_b32_e32 v0, s0
	s_waitcnt vmcnt(0) expcnt(0) lgkmcnt(0)
	ds_read_b32 v2, v0
	s_add_i32 s0, 0, 0x27ff4
	v_mov_b32_e32 v0, s0
	ds_read_b32 v0, v0
	s_waitcnt lgkmcnt(1)
	v_cmp_ne_u32_e32 vcc, 0, v2
	s_cbranch_vccnz .LBB0_578
	s_add_u32 s4, s30, 0x3f732200
	s_addc_u32 s5, s31, 0
	s_add_u32 s8, s30, 0x3f732400
	s_addc_u32 s9, s31, 0
	s_add_u32 s16, s30, 0x3f732500
	s_addc_u32 s17, s31, 0
	s_add_u32 s18, s30, 0x3f732600
	s_addc_u32 s19, s31, 0
	s_add_u32 s20, s30, 0x3f732700
	s_addc_u32 s21, s31, 0
	s_add_u32 s22, s30, 0x3f732800
	s_addc_u32 s23, s31, 0
	s_add_u32 s24, s30, 0x3f732900
	s_addc_u32 s25, s31, 0
	s_add_u32 s26, s30, 0x3f732a00
	s_addc_u32 s27, s31, 0
	s_add_u32 s36, s30, 0x3f732b00
	s_addc_u32 s37, s31, 0
	s_add_u32 s38, s30, 0x3f732c00
	s_addc_u32 s39, s31, 0
	s_add_u32 s40, s30, 0x3f732d00
	s_addc_u32 s41, s31, 0
	s_add_u32 s42, s30, 0x3f732e00
	s_addc_u32 s43, s31, 0
	s_add_u32 s44, s30, 0x3f732f00
	s_addc_u32 s45, s31, 0
	s_add_u32 s46, s30, 0x3f733000
	s_addc_u32 s47, s31, 0
	s_add_u32 s48, s30, 0x3f733100
	s_addc_u32 s49, s31, 0
	s_add_u32 s50, s30, 0x3f733200
	s_addc_u32 s51, s31, 0
	s_mul_i32 s33, s11, s87
	s_add_u32 s52, s30, 0x3f733300
	s_mul_i32 s33, s33, s10
	s_addc_u32 s53, s31, 0
	s_mov_b32 s60, 1
	v_mov_b32_e32 v16, 0
	s_branch .LBB0_566

; template <int LO, int HI>
; __global__ void __launch_bounds__(512) fwd_kernel(Params P) {
	.amdhsa_kernel _Z10fwd_kernelILi0ELi6EEv7ParamsK
		.amdhsa_group_segment_fixed_size 0
		.amdhsa_private_segment_fixed_size 0
		.amdhsa_kernarg_size 464
		.amdhsa_user_sgpr_count 2
		.amdhsa_user_sgpr_dispatch_ptr 0
		.amdhsa_user_sgpr_queue_ptr 0
		.amdhsa_user_sgpr_kernarg_segment_ptr 1
		.amdhsa_user_sgpr_dispatch_id 0
		.amdhsa_user_sgpr_kernarg_preload_length 0
		.amdhsa_user_sgpr_kernarg_preload_offset 0
		.amdhsa_user_sgpr_private_segment_size 0
		.amdhsa_uses_dynamic_stack 0
		.amdhsa_enable_private_segment 0
		.amdhsa_system_sgpr_workgroup_id_x 1
		.amdhsa_system_sgpr_workgroup_id_y 0
		.amdhsa_system_sgpr_workgroup_id_z 0
		.amdhsa_system_sgpr_workgroup_info 0
		.amdhsa_system_vgpr_workitem_id 2
		.amdhsa_next_free_vgpr 256
		.amdhsa_next_free_sgpr 98
		.amdhsa_accum_offset 256
		.amdhsa_reserve_vcc 1
		.amdhsa_float_round_mode_32 0
		.amdhsa_float_round_mode_16_64 0
		.amdhsa_float_denorm_mode_32 3
		.amdhsa_float_denorm_mode_16_64 3
		.amdhsa_dx10_clamp 1
		.amdhsa_ieee_mode 1
		.amdhsa_fp16_overflow 0
		.amdhsa_tg_split 0
		.amdhsa_exception_fp_ieee_invalid_op 0
		.amdhsa_exception_fp_denorm_src 0
		.amdhsa_exception_fp_ieee_div_zero 0
		.amdhsa_exception_fp_ieee_overflow 0
		.amdhsa_exception_fp_ieee_underflow 0
		.amdhsa_exception_fp_ieee_inexact 0
		.amdhsa_exception_int_div_zero 0
	.end_amdhsa_kernel

; template <int LO, int HI>
; __global__ void __launch_bounds__(512) fwd_kernel(Params P) {
amdhsa.kernels:
  - .agpr_count:     0
    .args:
      - .offset:         0
        .size:           208
        .value_kind:     by_value
      - .offset:         208
        .size:           4
        .value_kind:     hidden_block_count_x
      - .offset:         212
        .size:           4
        .value_kind:     hidden_block_count_y
      - .offset:         216
        .size:           4
        .value_kind:     hidden_block_count_z
      - .offset:         220
        .size:           2
        .value_kind:     hidden_group_size_x
      - .offset:         222
        .size:           2
        .value_kind:     hidden_group_size_y
      - .offset:         224
        .size:           2
        .value_kind:     hidden_group_size_z
      - .offset:         226
        .size:           2
        .value_kind:     hidden_remainder_x
      - .offset:         228
        .size:           2
        .value_kind:     hidden_remainder_y
      - .offset:         230
        .size:           2
        .value_kind:     hidden_remainder_z
      - .offset:         248
        .size:           8
        .value_kind:     hidden_global_offset_x
      - .offset:         256
        .size:           8
        .value_kind:     hidden_global_offset_y
      - .offset:         264
        .size:           8
        .value_kind:     hidden_global_offset_z
      - .offset:         272
        .size:           2
        .value_kind:     hidden_grid_dims
      - .offset:         296
        .size:           8
        .value_kind:     hidden_multigrid_sync_arg
      - .offset:         328
        .size:           4
        .value_kind:     hidden_dynamic_lds_size
    .group_segment_fixed_size: 0
    .kernarg_segment_align: 8
    .kernarg_segment_size: 464
    .language:       OpenCL C
    .language_version:
      - 2
      - 0
    .max_flat_workgroup_size: 512
    .name:           _Z10fwd_kernelILi0ELi6EEv7ParamsK
    .private_segment_fixed_size: 0
    .sgpr_count:     104
    .sgpr_spill_count: 3
    .symbol:         _Z10fwd_kernelILi0ELi6EEv7ParamsK.kd
    .uniform_work_group_size: 1
    .uses_dynamic_stack: false
    .vgpr_count:     256
    .vgpr_spill_count: 0
    .wavefront_size: 64
